# K-split exchange pipelined (counted vmcnt, 12 loads in flight) + faster flag poll, on top of Fm 4-row table + QK fusion
# baseline (speedup 1.0000x reference)
; #define PG8_LDA(dst, b, h) do { _Pragma("unroll") for (int m = 0; m < 4; ++m) _Pragma("unroll") for (int k = 0; k < 2; ++k) dst[m][k] = *(const LAS bf16x8*)(lds + PG8_SA(b, h) + aoff + m * 2048 + k * 1024); } while (0)
; template <class Epi, class Sched>
; __device__ __forceinline__ void gemm_phase(LAS unsigned char* lds_in, const int lda, const int ldb, const Sched& S, const Epi& E, const int WID) {
;     ...
;         for (int sg = 0; sg < (Epi::HAS_MID ? 3 : 1); ++sg) {
;         const int tb = Epi::HAS_MID ? (sg == 0 ? 0 : (sg == 1 ? 16 : 24)) : 0, te = Epi::HAS_MID ? (sg == 0 ? 16 : (sg == 1 ? 24 : nt)) : nt;
;         if constexpr (Epi::HAS_MID) { if (sg > 0) { PG8_SCHED; E.mid(acc, cur, tb, wr, wc, fr, fq); PG8_SCHED; } }
;         for (int t = tb; t < te; t += 2) {
;             const bool last = (t == nt - 2);
;             const char* a1 = cA + (size_t)(t + 1) * kstep;
;             const char* a2 = last ? nA : cA + (size_t)(t + 2) * kstep; const char* b2 = last ? nB : cB + (size_t)(t + 2) * kstep;
;             const char* a3 = a2 + kstep; const char* b3 = b2 + kstep;
;             PG8_LDB(B0, 0, 0); PG8_SCHED; PG8_LDA(At, 0, 0); PG8_STAGE(PG8_SA(1, 1), a1 + hstepA, voffA);
;             PG8_WAIT_L(8); PG8_BAR; PG8_WAIT_L(0); PG8_MMA(0, 0, At, B0); PG8_BAR; PG8_SCHED;
;             PG8_LDB(B1, 0, 1); PG8_STAGE(PG8_SB(0, 0), b2, voffB);
;             PG8_BAR; PG8_WAIT_L(0); PG8_MMA(0, 1, At, B1); PG8_BAR;
;             PG8_LDA(At, 0, 1); PG8_STAGE(PG8_SA(0, 0), a2, voffA);
;             PG8_BAR; PG8_WAIT_L(0); PG8_MMA(1, 0, At, B0); PG8_BAR; PG8_SCHED;
;             PG8_STAGE(PG8_SB(0, 1), b2 + hstepB, voffB);
;             PG8_WAIT_V(6); PG8_BAR; PG8_MMA(1, 1, At, B1); PG8_BAR;
;             PG8_LDB(B0, 1, 0); PG8_SCHED; PG8_LDA(At, 1, 0); PG8_STAGE(PG8_SA(0, 1), a2 + hstepA, voffA);
;             PG8_WAIT_L(8); PG8_BAR; PG8_WAIT_L(0); PG8_MMA(0, 0, At, B0); PG8_BAR; PG8_SCHED;
;             PG8_LDB(B1, 1, 1); PG8_STAGE(PG8_SB(1, 0), b3, voffB);
;             PG8_BAR; PG8_WAIT_L(0); PG8_MMA(0, 1, At, B1); PG8_BAR;
;             PG8_LDA(At, 1, 1); PG8_STAGE(PG8_SA(1, 0), a3, voffA);
;             PG8_BAR; PG8_WAIT_L(0); PG8_MMA(1, 0, At, B0); PG8_BAR; PG8_SCHED;
;             PG8_STAGE(PG8_SB(1, 1), b3 + hstepB, voffB);
;             PG8_WAIT_V(6); PG8_BAR; PG8_MMA(1, 1, At, B1); PG8_BAR;
;         }
;         }
;         E(acc, cur, wr, wc, fr, fq);
.Lks_spin:
	global_load_dword v132, v170, s[20:21] sc0 sc1
	s_waitcnt vmcnt(0)
	v_readfirstlane_b32 vcc_lo, v132
	s_cmp_eq_u32 vcc_lo, s22
	s_cbranch_scc1 .Lks_got
	s_add_i32 s23, s23, 1
	s_cmp_lt_u32 s23, 0x8000
	s_cbranch_scc0 .Lks_got
	s_sleep 1
	s_branch .Lks_spin
.Lks_got:
	global_load_dwordx4 v[178:181], v162, s[18:19] offset:0 sc0 sc1
	global_load_dwordx4 v[182:185], v162, s[18:19] offset:1024 sc0 sc1
	global_load_dwordx4 v[186:189], v162, s[18:19] offset:2048 sc0 sc1
	global_load_dwordx4 v[190:193], v162, s[18:19] offset:3072 sc0 sc1
	global_load_dwordx4 v[194:197], v163, s[18:19] offset:0 sc0 sc1
	global_load_dwordx4 v[198:201], v163, s[18:19] offset:1024 sc0 sc1
	global_load_dwordx4 v[202:205], v163, s[18:19] offset:2048 sc0 sc1
	global_load_dwordx4 v[206:209], v163, s[18:19] offset:3072 sc0 sc1
	global_load_dwordx4 v[130:133], v164, s[18:19] offset:0 sc0 sc1
	global_load_dwordx4 v[134:137], v164, s[18:19] offset:1024 sc0 sc1
	global_load_dwordx4 v[138:141], v164, s[18:19] offset:2048 sc0 sc1
	global_load_dwordx4 v[142:145], v164, s[18:19] offset:3072 sc0 sc1
	s_waitcnt vmcnt(4)
	v_pk_add_f32 v[2:3], v[2:3], v[178:179]
	v_pk_add_f32 v[4:5], v[4:5], v[180:181]
	v_pk_add_f32 v[6:7], v[6:7], v[182:183]
	v_pk_add_f32 v[8:9], v[8:9], v[184:185]
	v_pk_add_f32 v[10:11], v[10:11], v[186:187]
	v_pk_add_f32 v[12:13], v[12:13], v[188:189]
	v_pk_add_f32 v[14:15], v[14:15], v[190:191]
	v_pk_add_f32 v[16:17], v[16:17], v[192:193]
	v_pk_add_f32 v[18:19], v[18:19], v[194:195]
	v_pk_add_f32 v[20:21], v[20:21], v[196:197]
	v_pk_add_f32 v[22:23], v[22:23], v[198:199]
	v_pk_add_f32 v[24:25], v[24:25], v[200:201]
	v_pk_add_f32 v[26:27], v[26:27], v[202:203]
	v_pk_add_f32 v[28:29], v[28:29], v[204:205]
	v_pk_add_f32 v[30:31], v[30:31], v[206:207]
	v_pk_add_f32 v[32:33], v[32:33], v[208:209]
	global_load_dwordx4 v[178:181], v165, s[18:19] offset:0 sc0 sc1
	global_load_dwordx4 v[182:185], v165, s[18:19] offset:1024 sc0 sc1
	global_load_dwordx4 v[186:189], v165, s[18:19] offset:2048 sc0 sc1
	global_load_dwordx4 v[190:193], v165, s[18:19] offset:3072 sc0 sc1
	global_load_dwordx4 v[194:197], v166, s[18:19] offset:0 sc0 sc1
	global_load_dwordx4 v[198:201], v166, s[18:19] offset:1024 sc0 sc1
	global_load_dwordx4 v[202:205], v166, s[18:19] offset:2048 sc0 sc1
	global_load_dwordx4 v[206:209], v166, s[18:19] offset:3072 sc0 sc1
	s_waitcnt vmcnt(8)
	v_pk_add_f32 v[34:35], v[34:35], v[130:131]
	v_pk_add_f32 v[36:37], v[36:37], v[132:133]
	v_pk_add_f32 v[38:39], v[38:39], v[134:135]
	v_pk_add_f32 v[40:41], v[40:41], v[136:137]
	v_pk_add_f32 v[42:43], v[42:43], v[138:139]
	v_pk_add_f32 v[44:45], v[44:45], v[140:141]
	v_pk_add_f32 v[46:47], v[46:47], v[142:143]
	v_pk_add_f32 v[48:49], v[48:49], v[144:145]
	global_load_dwordx4 v[130:133], v167, s[18:19] offset:0 sc0 sc1
	global_load_dwordx4 v[134:137], v167, s[18:19] offset:1024 sc0 sc1
	global_load_dwordx4 v[138:141], v167, s[18:19] offset:2048 sc0 sc1
	global_load_dwordx4 v[142:145], v167, s[18:19] offset:3072 sc0 sc1
	s_waitcnt vmcnt(4)
	v_pk_add_f32 v[50:51], v[50:51], v[178:179]
	v_pk_add_f32 v[52:53], v[52:53], v[180:181]
	v_pk_add_f32 v[54:55], v[54:55], v[182:183]
	v_pk_add_f32 v[56:57], v[56:57], v[184:185]
	v_pk_add_f32 v[58:59], v[58:59], v[186:187]
	v_pk_add_f32 v[60:61], v[60:61], v[188:189]
	v_pk_add_f32 v[62:63], v[62:63], v[190:191]
	v_pk_add_f32 v[64:65], v[64:65], v[192:193]
	v_pk_add_f32 v[66:67], v[66:67], v[194:195]
	v_pk_add_f32 v[68:69], v[68:69], v[196:197]
	v_pk_add_f32 v[70:71], v[70:71], v[198:199]
	v_pk_add_f32 v[72:73], v[72:73], v[200:201]
	v_pk_add_f32 v[74:75], v[74:75], v[202:203]
	v_pk_add_f32 v[76:77], v[76:77], v[204:205]
	v_pk_add_f32 v[78:79], v[78:79], v[206:207]
	v_pk_add_f32 v[80:81], v[80:81], v[208:209]
	global_load_dwordx4 v[178:181], v168, s[18:19] offset:0 sc0 sc1
	global_load_dwordx4 v[182:185], v168, s[18:19] offset:1024 sc0 sc1
	global_load_dwordx4 v[186:189], v168, s[18:19] offset:2048 sc0 sc1
	global_load_dwordx4 v[190:193], v168, s[18:19] offset:3072 sc0 sc1
	global_load_dwordx4 v[194:197], v169, s[18:19] offset:0 sc0 sc1
	global_load_dwordx4 v[198:201], v169, s[18:19] offset:1024 sc0 sc1
	global_load_dwordx4 v[202:205], v169, s[18:19] offset:2048 sc0 sc1
	global_load_dwordx4 v[206:209], v169, s[18:19] offset:3072 sc0 sc1
	s_waitcnt vmcnt(8)
	v_pk_add_f32 v[82:83], v[82:83], v[130:131]
	v_pk_add_f32 v[84:85], v[84:85], v[132:133]
	v_pk_add_f32 v[86:87], v[86:87], v[134:135]
	v_pk_add_f32 v[88:89], v[88:89], v[136:137]
	v_pk_add_f32 v[90:91], v[90:91], v[138:139]
	v_pk_add_f32 v[92:93], v[92:93], v[140:141]
	v_pk_add_f32 v[94:95], v[94:95], v[142:143]
	v_pk_add_f32 v[96:97], v[96:97], v[144:145]
	s_waitcnt vmcnt(0)
	v_pk_add_f32 v[98:99], v[98:99], v[178:179]
	v_pk_add_f32 v[100:101], v[100:101], v[180:181]
	v_pk_add_f32 v[102:103], v[102:103], v[182:183]
	v_pk_add_f32 v[104:105], v[104:105], v[184:185]
	v_pk_add_f32 v[106:107], v[106:107], v[186:187]
	v_pk_add_f32 v[108:109], v[108:109], v[188:189]
	v_pk_add_f32 v[110:111], v[110:111], v[190:191]
	v_pk_add_f32 v[112:113], v[112:113], v[192:193]
	v_pk_add_f32 v[114:115], v[114:115], v[194:195]
	v_pk_add_f32 v[116:117], v[116:117], v[196:197]
	v_pk_add_f32 v[118:119], v[118:119], v[198:199]
	v_pk_add_f32 v[120:121], v[120:121], v[200:201]
	v_pk_add_f32 v[122:123], v[122:123], v[202:203]
	v_pk_add_f32 v[124:125], v[124:125], v[204:205]
	v_pk_add_f32 v[126:127], v[126:127], v[206:207]
	v_pk_add_f32 v[128:129], v[128:129], v[208:209]
